# phase 11: next unit's Q / tile / bias loads issued before the current unit's normalise-and-store epilogue (counted vmcnt accounts for the trailing stores)
# baseline (speedup 1.0000x reference)
; __device__ __forceinline__ void phase_na(const Params& p, unsigned char* lds) {
;     const int tid = threadIdx.x, lane = tid & 63, w = __builtin_amdgcn_readfirstlane(tid >> 6), fr = lane & 15, fq = lane >> 4;
;     bf16_t* KtB = (bf16_t*)(lds + NA_KT); bf16_t* vtB = (bf16_t*)(lds + NA_VT); bf16_t* Pw = (bf16_t*)(lds + NA_PW) + w * (32 * 72); float* rbt = (float*)(lds + NA_RB);
;     const bf16_t* QK = (const bf16_t*)(p.ws + WS_P); const bf16_t* VTg = (const bf16_t*)(p.ws + WS_VT); bf16_t* O = (bf16_t*)(p.ws + WS_A);
;     const int key = tid >> 3, part = tid & 7;
;     const int vd = tid >> 2, vc4 = tid & 3;
;     const float scale = 0.08838834764831845f * 1.4426950408889634f;
;     for (int u = blockIdx.x; u < 1024; u += gridDim.x) {
;         const int r4 = u & 15, h = (u >> 4) & 15, b = u >> 8, r0 = 4 * r4;
;         const int rs_lo = min(max(r0 - 4, 0), 56), rs_hi = min(max(r0 - 1, 0), 56);
;         const int ntile = 4 + (rs_hi + 8 - rs_lo);
;         const int qr = r0 + (w >> 1), qc0 = 32 * (w & 1);
;         const int rsq = min(max(qr - 4, 0), 56);
;     ...
;                 const int wlo0 = min(max(qc0 - 8, 0), 48), whi0 = min(max(qc0 + 7, 0), 48) + 16, wlo1 = min(max(qc0 + 8, 0), 48), whi1 = min(max(qc0 + 23, 0), 48) + 16;
; #pragma unroll
;                 for (int nt = 0; nt < 4; ++nt) {
;                     const bool act0 = !band || (16 * nt < whi0 && 16 * nt + 16 > wlo0), act1 = !band || (16 * nt < whi1 && 16 * nt + 16 > wlo1);
;                     st[0][nt] = (f32x4){0.f, 0.f, 0.f, 0.f}; st[1][nt] = (f32x4){0.f, 0.f, 0.f, 0.f};
;                     if (act0 || act1) {
;                         bf16x8 Bk[4];
; #pragma unroll
;                         for (int ks = 0; ks < 4; ++ks) Bk[ks] = *(const bf16x8*)(Kt + (nt * 16 + fr) * 136 + ks * 32 + fq * 8);
; #pragma unroll
;                         for (int ks = 0; ks < 4; ++ks) {
;                             if (act0) st[0][nt] = __builtin_amdgcn_mfma_f32_16x16x32_bf16(Bk[ks], aq[0][ks], st[0][nt], 0, 0, 0);
;                             if (act1) st[1][nt] = __builtin_amdgcn_mfma_f32_16x16x32_bf16(Bk[ks], aq[1][ks], st[1][nt], 0, 0, 0); }
;                     }
;                 }
;                 unsigned pk[2][4][2];
; #pragma unroll
;                 for (int mt = 0; mt < 2; ++mt) {
;                     __builtin_amdgcn_sched_barrier(0);
.Lna_begin:
	v_readfirstlane_b32 s10, v162
	s_add_u32 s4, s90, 0x10a00000
	s_addc_u32 s5, s91, 0
	s_add_u32 s6, s90, 0x19c00000
	s_addc_u32 s7, s91, 0
	s_add_u32 s8, s90, 0xc600000
	s_addc_u32 s9, s91, 0
	s_lshr_b32 s10, s10, 6
	s_lshr_b32 s11, s10, 1
	s_and_b32 s12, s10, 1
	s_lshl_b32 s12, s12, 5
	s_mov_b32 s30, 0x3e0293ee
	s_mov_b32 s31, 0xf149f2ca
	v_and_b32_e32 v232, 63, v162
	v_and_b32_e32 v233, 15, v232
	v_lshrrev_b32_e32 v234, 4, v232
	v_lshrrev_b32_e32 v235, 3, v162
	v_and_b32_e32 v236, 7, v162
	v_lshlrev_b32_e32 v237, 5, v236
	v_lshl_or_b32 v163, v235, 13, v237
	v_mul_u32_u24_e32 v238, 0x110, v235
	v_add_u32_e32 v164, v238, v237
	v_lshrrev_b32_e32 v235, 2, v162
	v_and_b32_e32 v236, 3, v162
	v_lshlrev_b32_e32 v237, 5, v236
	v_mul_u32_u24_e32 v238, 0x8800, v235
	v_add_u32_e32 v165, v238, v237
	v_mul_u32_u24_e32 v238, 0x90, v235
	v_add_u32_e32 v238, v238, v237
	v_add_u32_e32 v166, 52224, v238
	v_mul_u32_u24_e32 v238, 0x110, v233
	v_lshl_add_u32 v167, v234, 4, v238
	v_mul_u32_u24_e32 v238, 0x90, v233
	v_lshl_add_u32 v238, v234, 3, v238
	v_add_u32_e32 v168, 52224, v238
	v_xor_b32_e32 v235, 16, v232
	v_lshlrev_b32_e32 v218, 2, v235
	v_xor_b32_e32 v235, 32, v232
	v_lshlrev_b32_e32 v219, 2, v235
	v_mov_b32_e32 v232, 0
	v_mov_b32_e32 v239, 0xf149f2ca
	v_add_u32_e32 v235, s12, v233
	v_sub_u32_e64 v236, v235, 8 clamp
	v_min_u32_e32 v236, 48, v236
	v_lshlrev_b32_e32 v237, 2, v234
	v_sub_u32_e32 v238, v237, v235
	v_lshlrev_b32_e32 v238, 2, v238
	v_add_u32_e32 v220, 110908, v238
	v_sub_u32_e32 v238, v237, v236
	v_add_u32_e32 v237, 0, v238
	v_cmp_gt_u32_e32 vcc, 16, v237
	v_cndmask_b32_e32 v186, v239, v232, vcc
	v_add_u32_e32 v237, 1, v238
	v_cmp_gt_u32_e32 vcc, 16, v237
	v_cndmask_b32_e32 v187, v239, v232, vcc
	v_add_u32_e32 v237, 2, v238
	v_cmp_gt_u32_e32 vcc, 16, v237
	v_cndmask_b32_e32 v188, v239, v232, vcc
	v_add_u32_e32 v237, 3, v238
	v_cmp_gt_u32_e32 vcc, 16, v237
	v_cndmask_b32_e32 v189, v239, v232, vcc
	v_add_u32_e32 v237, 16, v238
	v_cmp_gt_u32_e32 vcc, 16, v237
	v_cndmask_b32_e32 v190, v239, v232, vcc
	v_add_u32_e32 v237, 17, v238
	v_cmp_gt_u32_e32 vcc, 16, v237
	v_cndmask_b32_e32 v191, v239, v232, vcc
	v_add_u32_e32 v237, 18, v238
	v_cmp_gt_u32_e32 vcc, 16, v237
	v_cndmask_b32_e32 v192, v239, v232, vcc
	v_add_u32_e32 v237, 19, v238
	v_cmp_gt_u32_e32 vcc, 16, v237
	v_cndmask_b32_e32 v193, v239, v232, vcc
	v_add_u32_e32 v237, 32, v238
	v_cmp_gt_u32_e32 vcc, 16, v237
	v_cndmask_b32_e32 v194, v239, v232, vcc
	v_add_u32_e32 v237, 33, v238
	v_cmp_gt_u32_e32 vcc, 16, v237
	v_cndmask_b32_e32 v195, v239, v232, vcc
	v_add_u32_e32 v237, 34, v238
	v_cmp_gt_u32_e32 vcc, 16, v237
	v_cndmask_b32_e32 v196, v239, v232, vcc
	v_add_u32_e32 v237, 35, v238
	v_cmp_gt_u32_e32 vcc, 16, v237
	v_cndmask_b32_e32 v197, v239, v232, vcc
	v_add_u32_e32 v237, 48, v238
	v_cmp_gt_u32_e32 vcc, 16, v237
	v_cndmask_b32_e32 v198, v239, v232, vcc
	v_add_u32_e32 v237, 49, v238
	v_cmp_gt_u32_e32 vcc, 16, v237
	v_cndmask_b32_e32 v199, v239, v232, vcc
	v_add_u32_e32 v237, 50, v238
	v_cmp_gt_u32_e32 vcc, 16, v237
	v_cndmask_b32_e32 v200, v239, v232, vcc
	v_add_u32_e32 v237, 51, v238
	v_cmp_gt_u32_e32 vcc, 16, v237
	v_cndmask_b32_e32 v201, v239, v232, vcc
	v_add_u32_e32 v235, s12, v233
	v_add_u32_e32 v235, 16, v235
	v_sub_u32_e64 v236, v235, 8 clamp
	v_min_u32_e32 v236, 48, v236
	v_lshlrev_b32_e32 v237, 2, v234
	v_sub_u32_e32 v238, v237, v235
	v_lshlrev_b32_e32 v238, 2, v238
	v_add_u32_e32 v221, 110908, v238
	v_sub_u32_e32 v238, v237, v236
	v_add_u32_e32 v237, 0, v238
	v_cmp_gt_u32_e64 s[32:33], 16, v237
	v_add_u32_e32 v237, 1, v238
	v_cmp_gt_u32_e64 s[34:35], 16, v237
	v_add_u32_e32 v237, 2, v238
	v_cmp_gt_u32_e64 s[36:37], 16, v237
	v_add_u32_e32 v237, 3, v238
	v_cmp_gt_u32_e64 s[38:39], 16, v237
	v_add_u32_e32 v237, 16, v238
	v_cmp_gt_u32_e64 s[40:41], 16, v237
	v_add_u32_e32 v237, 17, v238
	v_cmp_gt_u32_e64 s[42:43], 16, v237
	v_add_u32_e32 v237, 18, v238
	v_cmp_gt_u32_e64 s[44:45], 16, v237
	v_add_u32_e32 v237, 19, v238
	v_cmp_gt_u32_e64 s[46:47], 16, v237
	v_add_u32_e32 v237, 32, v238
	v_cmp_gt_u32_e64 s[48:49], 16, v237
	v_add_u32_e32 v237, 33, v238
	v_cmp_gt_u32_e64 s[50:51], 16, v237
	v_add_u32_e32 v237, 34, v238
	v_cmp_gt_u32_e64 s[52:53], 16, v237
	v_add_u32_e32 v237, 35, v238
	v_cmp_gt_u32_e64 s[54:55], 16, v237
	v_add_u32_e32 v237, 48, v238
	v_cmp_gt_u32_e64 s[56:57], 16, v237
	v_add_u32_e32 v237, 49, v238
	v_cmp_gt_u32_e64 s[58:59], 16, v237
	v_add_u32_e32 v237, 50, v238
	v_cmp_gt_u32_e64 s[60:61], 16, v237
	v_add_u32_e32 v237, 51, v238
	v_cmp_gt_u32_e64 s[62:63], 16, v237
	v_lshlrev_b32_e32 v235, 2, v162
	v_add_u32_e32 v235, 110592, v235
	v_mov_b32_e32 v236, 0
	ds_write_b32 v235, v236
	v_cmp_gt_u32_e32 vcc, 128, v162
	s_and_saveexec_b64 s[0:1], vcc
	ds_write_b32 v235, v236 offset:2048
	s_mov_b64 exec, s[0:1]
	s_mov_b32 s13, s92
	s_waitcnt lgkmcnt(0)
	s_cmp_ge_u32 s13, 0x400
	s_cbranch_scc1 .Lna_done
; #define NA_WRITE(R, buf) do { bf16_t* kd = KtB + (buf) * (64 * 136) + key * 136 + part * 16; bf16_t* vdp = vtB + (buf) * (128 * 72) + vd * 72 + vc4 * 16; \
;         *(u32x4*)kd = R[0]; *(u32x4*)(kd + 8) = R[1]; *(u32x4*)vdp = R[2]; *(u32x4*)(vdp + 8) = R[3]; } while (0)
; __device__ __forceinline__ void phase_na(const Params& p, unsigned char* lds) {
;     ...
;     for (int u = blockIdx.x; u < 1024; u += gridDim.x) {
;         const int r4 = u & 15, h = (u >> 4) & 15, b = u >> 8, r0 = 4 * r4;
;         const int rs_lo = min(max(r0 - 4, 0), 56), rs_hi = min(max(r0 - 1, 0), 56);
;         const int ntile = 4 + (rs_hi + 8 - rs_lo);
;         const int qr = r0 + (w >> 1), qc0 = 32 * (w & 1);
;         const int rsq = min(max(qr - 4, 0), 56);
;         __syncthreads();
;         for (int e = tid; e < 465; e += 512) rbt[e] = p.rel_bias[h * 465 + e] * 1.4426950408889634f;
;         bf16x8 aq[2][4];
; #pragma unroll
;         for (int mt = 0; mt < 2; ++mt) { const bf16_t* qp = QK + (size_t)(b * SEQ + qr * 64 + qc0 + 16 * mt + fr) * NQK + h * 128 + fq * 8;
; #pragma unroll
;             for (int ks = 0; ks < 4; ++ks) aq[mt][ks] = *(const bf16x8*)(qp + ks * 32); }
;         f32x4 Oa[2][8];
; #pragma unroll
;         for (int mt = 0; mt < 2; ++mt)
; #pragma unroll
;             for (int dt = 0; dt < 8; ++dt) Oa[mt][dt] = (f32x4){0.f, 0.f, 0.f, 0.f};
;         float mrow[2] = {-1e30f, -1e30f}, lrow[2] = {0.f, 0.f};
;         u32x4 ra[4];
;     ...
;         { u32x4 rn[4];
;           NA_LOAD(ra, 0); NA_LOAD(rn, 1); NA_WRITE(ra, 0);
;           ra[0] = rn[0]; ra[1] = rn[1]; ra[2] = rn[2]; ra[3] = rn[3]; }
;         __syncthreads();
	s_lshr_b32 s15, s13, 8
	s_and_b32 s0, s13, 7
	s_bfe_u32 s1, s13, 0x50003
	s_lshr_b32 s14, s1, 4
	s_lshl_b32 s0, s0, 1
	s_or_b32 s14, s14, s0
	s_and_b32 s16, s1, 15
	s_lshl_b32 s16, s16, 2
	s_add_i32 s17, s16, -4
	s_max_i32 s17, s17, 0
	s_min_i32 s17, s17, 56
	s_add_i32 s18, s16, -1
	s_max_i32 s18, s18, 0
	s_min_i32 s18, s18, 56
	s_sub_i32 s18, s18, s17
	s_add_i32 s18, s18, 12
	s_add_i32 s19, s16, s11
	s_add_i32 s20, s19, -4
	s_max_i32 s20, s20, 0
	s_min_i32 s20, s20, 56
	s_movk_i32 s0, 0x1d1
	v_cmp_gt_u32_e32 vcc, s0, v162
	s_and_saveexec_b64 s[2:3], vcc
	s_mul_i32 s0, s14, 0x1d1
	v_add_lshl_u32 v238, s0, v162, 2
	global_load_dword v240, v238, s[84:85]
	s_mov_b64 exec, s[2:3]
	s_mov_b32 s21, 0
	s_lshl_b32 s28, s15, 8
	s_add_i32 s28, s28, 0x4000
	s_lshl_b32 s29, s21, 6
	s_add_i32 s28, s28, s29
	s_add_i32 s29, s21, s17
	s_add_i32 s29, s29, -4
	s_lshl_b32 s29, s29, 6
	s_lshl_b32 s26, s15, 12
	s_add_i32 s29, s29, s26
	s_cmp_lt_u32 s21, 4
	s_cselect_b32 s28, s28, s29
	s_lshl_b32 s26, s28, 13
	s_lshl_b32 s29, s14, 8
	s_add_i32 s26, s26, s29
	s_add_i32 s26, s26, 0x1000
	s_lshl_b32 s27, s28, 1
	s_mul_i32 s29, s14, 0x440000
	s_add_i32 s27, s27, s29
	v_add_u32_e32 v238, s26, v163
	v_add_u32_e32 v239, s27, v165
	global_load_dwordx4 v[128:131], v238, s[4:5]
	global_load_dwordx4 v[132:135], v238, s[4:5] offset:16
	global_load_dwordx4 v[136:139], v239, s[6:7]
	global_load_dwordx4 v[140:143], v239, s[6:7] offset:16
	s_mov_b32 s21, 1
	s_lshl_b32 s28, s15, 8
	s_add_i32 s28, s28, 0x4000
	s_lshl_b32 s29, s21, 6
	s_add_i32 s28, s28, s29
	s_add_i32 s29, s21, s17
	s_add_i32 s29, s29, -4
	s_lshl_b32 s29, s29, 6
	s_lshl_b32 s26, s15, 12
	s_add_i32 s29, s29, s26
	s_cmp_lt_u32 s21, 4
	s_cselect_b32 s28, s28, s29
	s_lshl_b32 s26, s28, 13
	s_lshl_b32 s29, s14, 8
	s_add_i32 s26, s26, s29
	s_add_i32 s26, s26, 0x1000
	s_lshl_b32 s27, s28, 1
	s_mul_i32 s29, s14, 0x440000
	s_add_i32 s27, s27, s29
	v_add_u32_e32 v238, s26, v163
	v_add_u32_e32 v239, s27, v165
	global_load_dwordx4 v[202:205], v238, s[4:5]
	global_load_dwordx4 v[206:209], v238, s[4:5] offset:16
	global_load_dwordx4 v[210:213], v239, s[6:7]
	global_load_dwordx4 v[214:217], v239, s[6:7] offset:16
	s_lshl_b32 s0, s15, 12
	s_lshl_b32 s1, s19, 6
	s_add_i32 s0, s0, s1
	s_add_i32 s0, s0, s12
	v_and_b32_e32 v238, 15, v162
	v_bfe_u32 v239, v162, 4, 2
	v_add_u32_e32 v238, s0, v238
	v_lshlrev_b32_e32 v238, 13, v238
	v_lshl_add_u32 v238, v239, 4, v238
	s_lshl_b32 s1, s14, 8
	v_add_u32_e32 v238, s1, v238
	v_add_u32_e32 v239, 0x20000, v238
	global_load_dwordx4 v[0:3], v238, s[4:5] offset:0
	global_load_dwordx4 v[4:7], v238, s[4:5] offset:64
	global_load_dwordx4 v[8:11], v238, s[4:5] offset:128
	global_load_dwordx4 v[12:15], v238, s[4:5] offset:192
	global_load_dwordx4 v[16:19], v239, s[4:5] offset:0
	global_load_dwordx4 v[20:23], v239, s[4:5] offset:64
	global_load_dwordx4 v[24:27], v239, s[4:5] offset:128
	global_load_dwordx4 v[28:31], v239, s[4:5] offset:192
	s_mov_b32 s21, 2
	s_lshl_b32 s28, s15, 8
	s_add_i32 s28, s28, 0x4000
	s_lshl_b32 s29, s21, 6
	s_add_i32 s28, s28, s29
	s_add_i32 s29, s21, s17
	s_add_i32 s29, s29, -4
	s_lshl_b32 s29, s29, 6
	s_lshl_b32 s26, s15, 12
	s_add_i32 s29, s29, s26
	s_cmp_lt_u32 s21, 4
	s_cselect_b32 s28, s28, s29
	s_lshl_b32 s26, s28, 13
	s_lshl_b32 s29, s14, 8
	s_add_i32 s26, s26, s29
	s_add_i32 s26, s26, 0x1000
	s_lshl_b32 s27, s28, 1
	s_mul_i32 s29, s14, 0x440000
	s_add_i32 s27, s27, s29
	v_add_u32_e32 v238, s26, v163
	v_add_u32_e32 v239, s27, v165
	global_load_dwordx4 v[170:173], v238, s[4:5]
	global_load_dwordx4 v[174:177], v238, s[4:5] offset:16
	global_load_dwordx4 v[178:181], v239, s[6:7]
	global_load_dwordx4 v[182:185], v239, s[6:7] offset:16
	s_mov_b32 s67, 1
.Lna_unit:
	s_barrier
	v_mov_b32_e32 v32, 0
	v_mov_b32_e32 v33, 0
	v_mov_b32_e32 v34, 0
	v_mov_b32_e32 v35, 0
	v_mov_b32_e32 v36, 0
	v_mov_b32_e32 v37, 0
	v_mov_b32_e32 v38, 0
	v_mov_b32_e32 v39, 0
	v_mov_b32_e32 v40, 0
	v_mov_b32_e32 v41, 0
	v_mov_b32_e32 v42, 0
	v_mov_b32_e32 v43, 0
	v_mov_b32_e32 v44, 0
	v_mov_b32_e32 v45, 0
	v_mov_b32_e32 v46, 0
	v_mov_b32_e32 v47, 0
	v_mov_b32_e32 v48, 0
	v_mov_b32_e32 v49, 0
	v_mov_b32_e32 v50, 0
	v_mov_b32_e32 v51, 0
	v_mov_b32_e32 v52, 0
	v_mov_b32_e32 v53, 0
	v_mov_b32_e32 v54, 0
	v_mov_b32_e32 v55, 0
	v_mov_b32_e32 v56, 0
	v_mov_b32_e32 v57, 0
	v_mov_b32_e32 v58, 0
	v_mov_b32_e32 v59, 0
	v_mov_b32_e32 v60, 0
	v_mov_b32_e32 v61, 0
	v_mov_b32_e32 v62, 0
	v_mov_b32_e32 v63, 0
	v_mov_b32_e32 v64, 0
	v_mov_b32_e32 v65, 0
	v_mov_b32_e32 v66, 0
	v_mov_b32_e32 v67, 0
	v_mov_b32_e32 v68, 0
	v_mov_b32_e32 v69, 0
	v_mov_b32_e32 v70, 0
	v_mov_b32_e32 v71, 0
	v_mov_b32_e32 v72, 0
	v_mov_b32_e32 v73, 0
	v_mov_b32_e32 v74, 0
	v_mov_b32_e32 v75, 0
	v_mov_b32_e32 v76, 0
	v_mov_b32_e32 v77, 0
	v_mov_b32_e32 v78, 0
	v_mov_b32_e32 v79, 0
	v_mov_b32_e32 v80, 0
	v_mov_b32_e32 v81, 0
	v_mov_b32_e32 v82, 0
	v_mov_b32_e32 v83, 0
	v_mov_b32_e32 v84, 0
	v_mov_b32_e32 v85, 0
	v_mov_b32_e32 v86, 0
	v_mov_b32_e32 v87, 0
	v_mov_b32_e32 v88, 0
	v_mov_b32_e32 v89, 0
	v_mov_b32_e32 v90, 0
	v_mov_b32_e32 v91, 0
	v_mov_b32_e32 v92, 0
	v_mov_b32_e32 v93, 0
	v_mov_b32_e32 v94, 0
	v_mov_b32_e32 v95, 0
	v_mov_b32_e32 v222, 0xf149f2ca
	v_mov_b32_e32 v224, 0
	v_mov_b32_e32 v226, 0x7149f2ca
	v_mov_b32_e32 v223, 0xf149f2ca
	v_mov_b32_e32 v225, 0
	v_mov_b32_e32 v227, 0x7149f2ca
	s_movk_i32 s0, 0x1d1
	v_cmp_gt_u32_e32 vcc, s0, v162
	v_lshlrev_b32_e32 v235, 2, v162
	v_add_u32_e32 v235, 110848, v235
	s_cmp_eq_u32 s67, 1
	s_cbranch_scc0 .Lna_wb_next
	s_waitcnt vmcnt(20)
	s_branch .Lna_wb_done
.Lna_wb_next:
	s_waitcnt vmcnt(28)
.Lna_wb_done:
	s_and_saveexec_b64 s[2:3], vcc
	v_mul_f32_e32 v234, 0x413504f3, v240
	ds_write_b32 v235, v234
	s_mov_b64 exec, s[2:3]
	s_cmp_eq_u32 s67, 1
	s_cbranch_scc0 .Lna_wt_next
	s_waitcnt vmcnt(16)
	s_branch .Lna_wt_done
.Lna_wt_next:
	s_waitcnt vmcnt(24)
.Lna_wt_done:
	ds_write_b128 v164, v[128:131]
	ds_write_b128 v164, v[132:135] offset:16
	ds_write_b128 v166, v[136:139]
	ds_write_b128 v166, v[140:143] offset:16
	s_waitcnt lgkmcnt(0)
	s_barrier
	s_mov_b32 s21, 0
	s_mov_b32 s65, 0
	s_mov_b32 s66, 1

; #define NA_WRITE(R, buf) do { bf16_t* kd = KtB + (buf) * (64 * 136) + key * 136 + part * 16; bf16_t* vdp = vtB + (buf) * (128 * 72) + vd * 72 + vc4 * 16; \
;         *(u32x4*)kd = R[0]; *(u32x4*)(kd + 8) = R[1]; *(u32x4*)vdp = R[2]; *(u32x4*)(vdp + 8) = R[3]; } while (0)
; __device__ __forceinline__ void phase_na(const Params& p, unsigned char* lds) {
;     ...
;     for (int u = blockIdx.x; u < 1024; u += gridDim.x) {
;         const int r4 = u & 15, h = (u >> 4) & 15, b = u >> 8, r0 = 4 * r4;
;         const int rs_lo = min(max(r0 - 4, 0), 56), rs_hi = min(max(r0 - 1, 0), 56);
;         const int ntile = 4 + (rs_hi + 8 - rs_lo);
;         const int qr = r0 + (w >> 1), qc0 = 32 * (w & 1);
;         const int rsq = min(max(qr - 4, 0), 56);
;         __syncthreads();
;         for (int e = tid; e < 465; e += 512) rbt[e] = p.rel_bias[h * 465 + e] * 1.4426950408889634f;
;         bf16x8 aq[2][4];
; #pragma unroll
;         for (int mt = 0; mt < 2; ++mt) { const bf16_t* qp = QK + (size_t)(b * SEQ + qr * 64 + qc0 + 16 * mt + fr) * NQK + h * 128 + fq * 8;
; #pragma unroll
;             for (int ks = 0; ks < 4; ++ks) aq[mt][ks] = *(const bf16x8*)(qp + ks * 32); }
;         f32x4 Oa[2][8];
; #pragma unroll
;         for (int mt = 0; mt < 2; ++mt)
; #pragma unroll
;             for (int dt = 0; dt < 8; ++dt) Oa[mt][dt] = (f32x4){0.f, 0.f, 0.f, 0.f};
;         float mrow[2] = {-1e30f, -1e30f}, lrow[2] = {0.f, 0.f};
;         u32x4 ra[4];
;     ...
;         { u32x4 rn[4];
;           NA_LOAD(ra, 0); NA_LOAD(rn, 1); NA_WRITE(ra, 0);
;           ra[0] = rn[0]; ra[1] = rn[1]; ra[2] = rn[2]; ra[3] = rn[3]; }
;     ...
;             __syncthreads();
;         }
.Lna_tile_end:
	s_waitcnt lgkmcnt(0)
	s_barrier
	s_mov_b32 s65, s66
	s_add_i32 s66, s66, 1
	s_cmp_eq_u32 s66, 3
	s_cselect_b32 s66, 0, s66
	s_add_i32 s21, s21, 1
	s_cmp_lt_u32 s21, s18
	s_cbranch_scc1 .Lna_tile
	s_mul_i32 s0, s10, 0x2200
	v_and_b32_e32 v230, 15, v162
	v_mul_u32_u24_e32 v230, 0x110, v230
	v_bfe_u32 v239, v162, 4, 2
	v_lshl_add_u32 v230, v239, 3, v230
	v_add_u32_e32 v230, s0, v230
	v_and_b32_e32 v238, 63, v162
	v_lshrrev_b32_e32 v228, 1, v238
	v_and_b32_e32 v229, 1, v238
	v_mul_u32_u24_e32 v231, 0x110, v228
	v_lshl_add_u32 v231, v229, 7, v231
	v_add_u32_e32 v231, s0, v231
	s_lshl_b32 s0, s15, 12
	s_lshl_b32 s1, s19, 6
	s_add_i32 s0, s0, s1
	s_add_i32 s0, s0, s12
	v_add_u32_e32 v228, s0, v228
	v_lshlrev_b32_e32 v228, 12, v228
	v_lshl_add_u32 v228, v229, 7, v228
	s_lshl_b32 s1, s14, 8
	v_add_u32_e32 v228, s1, v228
	s_add_i32 s13, s13, s82
	s_mov_b32 s68, 0
	s_cmp_ge_u32 s13, 0x400
	s_cbranch_scc1 .Lna_nonext
	s_mov_b32 s68, 1
	s_lshr_b32 s15, s13, 8
	s_and_b32 s0, s13, 7
	s_bfe_u32 s1, s13, 0x50003
	s_lshr_b32 s14, s1, 4
	s_lshl_b32 s0, s0, 1
	s_or_b32 s14, s14, s0
	s_and_b32 s16, s1, 15
	s_lshl_b32 s16, s16, 2
	s_add_i32 s17, s16, -4
	s_max_i32 s17, s17, 0
	s_min_i32 s17, s17, 56
	s_add_i32 s18, s16, -1
	s_max_i32 s18, s18, 0
	s_min_i32 s18, s18, 56
	s_sub_i32 s18, s18, s17
	s_add_i32 s18, s18, 12
	s_add_i32 s19, s16, s11
	s_add_i32 s20, s19, -4
	s_max_i32 s20, s20, 0
	s_min_i32 s20, s20, 56
	s_movk_i32 s0, 0x1d1
	v_cmp_gt_u32_e32 vcc, s0, v162
	s_and_saveexec_b64 s[2:3], vcc
	s_mul_i32 s0, s14, 0x1d1
	v_add_lshl_u32 v238, s0, v162, 2
	global_load_dword v240, v238, s[84:85]
	s_mov_b64 exec, s[2:3]
	s_mov_b32 s21, 0
	s_lshl_b32 s28, s15, 8
	s_add_i32 s28, s28, 0x4000
	s_lshl_b32 s29, s21, 6
	s_add_i32 s28, s28, s29
	s_add_i32 s29, s21, s17
	s_add_i32 s29, s29, -4
	s_lshl_b32 s29, s29, 6
	s_lshl_b32 s26, s15, 12
	s_add_i32 s29, s29, s26
	s_cmp_lt_u32 s21, 4
	s_cselect_b32 s28, s28, s29
	s_lshl_b32 s26, s28, 13
	s_lshl_b32 s29, s14, 8
	s_add_i32 s26, s26, s29
	s_add_i32 s26, s26, 0x1000
	s_lshl_b32 s27, s28, 1
	s_mul_i32 s29, s14, 0x440000
	s_add_i32 s27, s27, s29
	v_add_u32_e32 v238, s26, v163
	v_add_u32_e32 v239, s27, v165
	global_load_dwordx4 v[128:131], v238, s[4:5]
	global_load_dwordx4 v[132:135], v238, s[4:5] offset:16
	global_load_dwordx4 v[136:139], v239, s[6:7]
	global_load_dwordx4 v[140:143], v239, s[6:7] offset:16
	s_mov_b32 s21, 1
	s_lshl_b32 s28, s15, 8
	s_add_i32 s28, s28, 0x4000
	s_lshl_b32 s29, s21, 6
	s_add_i32 s28, s28, s29
	s_add_i32 s29, s21, s17
	s_add_i32 s29, s29, -4
	s_lshl_b32 s29, s29, 6
	s_lshl_b32 s26, s15, 12
	s_add_i32 s29, s29, s26
	s_cmp_lt_u32 s21, 4
	s_cselect_b32 s28, s28, s29
	s_lshl_b32 s26, s28, 13
	s_lshl_b32 s29, s14, 8
	s_add_i32 s26, s26, s29
	s_add_i32 s26, s26, 0x1000
	s_lshl_b32 s27, s28, 1
	s_mul_i32 s29, s14, 0x440000
	s_add_i32 s27, s27, s29
	v_add_u32_e32 v238, s26, v163
	v_add_u32_e32 v239, s27, v165
	global_load_dwordx4 v[202:205], v238, s[4:5]
	global_load_dwordx4 v[206:209], v238, s[4:5] offset:16
	global_load_dwordx4 v[210:213], v239, s[6:7]
	global_load_dwordx4 v[214:217], v239, s[6:7] offset:16
	s_lshl_b32 s0, s15, 12
	s_lshl_b32 s1, s19, 6
	s_add_i32 s0, s0, s1
	s_add_i32 s0, s0, s12
	v_and_b32_e32 v238, 15, v162
	v_bfe_u32 v239, v162, 4, 2
	v_add_u32_e32 v238, s0, v238
	v_lshlrev_b32_e32 v238, 13, v238
	v_lshl_add_u32 v238, v239, 4, v238
	s_lshl_b32 s1, s14, 8
	v_add_u32_e32 v238, s1, v238
	v_add_u32_e32 v239, 0x20000, v238
	global_load_dwordx4 v[0:3], v238, s[4:5] offset:0
	global_load_dwordx4 v[4:7], v238, s[4:5] offset:64
	global_load_dwordx4 v[8:11], v238, s[4:5] offset:128
	global_load_dwordx4 v[12:15], v238, s[4:5] offset:192
	global_load_dwordx4 v[16:19], v239, s[4:5] offset:0
	global_load_dwordx4 v[20:23], v239, s[4:5] offset:64
	global_load_dwordx4 v[24:27], v239, s[4:5] offset:128
	global_load_dwordx4 v[28:31], v239, s[4:5] offset:192
	s_mov_b32 s21, 2
	s_lshl_b32 s28, s15, 8
	s_add_i32 s28, s28, 0x4000
	s_lshl_b32 s29, s21, 6
	s_add_i32 s28, s28, s29
	s_add_i32 s29, s21, s17
	s_add_i32 s29, s29, -4
	s_lshl_b32 s29, s29, 6
	s_lshl_b32 s26, s15, 12
	s_add_i32 s29, s29, s26
	s_cmp_lt_u32 s21, 4
	s_cselect_b32 s28, s28, s29
	s_lshl_b32 s26, s28, 13
	s_lshl_b32 s29, s14, 8
	s_add_i32 s26, s26, s29
	s_add_i32 s26, s26, 0x1000
	s_lshl_b32 s27, s28, 1
	s_mul_i32 s29, s14, 0x440000
	s_add_i32 s27, s27, s29
	v_add_u32_e32 v238, s26, v163
	v_add_u32_e32 v239, s27, v165
	global_load_dwordx4 v[170:173], v238, s[4:5]
	global_load_dwordx4 v[174:177], v238, s[4:5] offset:16
	global_load_dwordx4 v[178:181], v239, s[6:7]
	global_load_dwordx4 v[182:185], v239, s[6:7] offset:16
; __device__ __forceinline__ unsigned pk2(float lo, float hi) { return __builtin_bit_cast(unsigned, __builtin_convertvector((f32x2){lo, hi}, hwbf16x2)); }
; __device__ __forceinline__ void phase_na(const Params& p, unsigned char* lds) {
;     ...
;         { bf16_t* ost = KtB + w * (32 * 136);
; #pragma unroll
;           for (int mt = 0; mt < 2; ++mt) {
;             float l = lrow[mt]; l += __shfl_xor(l, 16); l += __shfl_xor(l, 32); const float inv = 1.f / l;
; #pragma unroll
;             for (int dt = 0; dt < 8; ++dt) *(u32x2*)(ost + (mt * 16 + fr) * 136 + dt * 16 + fq * 4) = (u32x2){pk2(Oa[mt][dt][0] * inv, Oa[mt][dt][1] * inv), pk2(Oa[mt][dt][2] * inv, Oa[mt][dt][3] * inv)}; }
;           asm volatile("s_waitcnt lgkmcnt(0)" ::: "memory");
;           const int q = lane >> 1, hf = lane & 1;
;           bf16_t* op = O + (size_t)(b * SEQ + qr * 64 + qc0 + q) * D + h * 128 + hf * 64;
; #pragma unroll
;           for (int e = 0; e < 8; ++e) *(u32x4*)(op + e * 8) = *(const u32x4*)(ost + q * 136 + hf * 64 + e * 8); }
.Lna_nonext:
	ds_bpermute_b32 v232, v218, v224
	ds_bpermute_b32 v233, v218, v225
	s_waitcnt lgkmcnt(0)
	v_add_f32_e32 v232, v232, v224
	v_add_f32_e32 v233, v233, v225
	ds_bpermute_b32 v234, v219, v232
	ds_bpermute_b32 v235, v219, v233
	s_waitcnt lgkmcnt(0)
	v_add_f32_e32 v232, v232, v234
	v_add_f32_e32 v233, v233, v235
	v_rcp_f32_e32 v234, v232
	s_nop 0
	v_fma_f32 v236, -v232, v234, 1.0
	v_fma_f32 v234, v236, v234, v234
	v_rcp_f32_e32 v235, v233
	s_nop 0
	v_fma_f32 v237, -v233, v235, 1.0
	v_fma_f32 v235, v237, v235, v235
	v_mul_f32_e32 v32, v32, v234
	v_mul_f32_e32 v33, v33, v234
	v_mul_f32_e32 v34, v34, v234
	v_mul_f32_e32 v35, v35, v234
	v_cvt_pk_bf16_f32 v32, v32, v33
	v_cvt_pk_bf16_f32 v33, v34, v35
	ds_write_b64 v230, v[32:33] offset:0
	v_mul_f32_e32 v36, v36, v234
	v_mul_f32_e32 v37, v37, v234
	v_mul_f32_e32 v38, v38, v234
	v_mul_f32_e32 v39, v39, v234
	v_cvt_pk_bf16_f32 v36, v36, v37
	v_cvt_pk_bf16_f32 v37, v38, v39
	ds_write_b64 v230, v[36:37] offset:32
	v_mul_f32_e32 v40, v40, v234
	v_mul_f32_e32 v41, v41, v234
	v_mul_f32_e32 v42, v42, v234
	v_mul_f32_e32 v43, v43, v234
	v_cvt_pk_bf16_f32 v40, v40, v41
	v_cvt_pk_bf16_f32 v41, v42, v43
	ds_write_b64 v230, v[40:41] offset:64
	v_mul_f32_e32 v44, v44, v234
	v_mul_f32_e32 v45, v45, v234
	v_mul_f32_e32 v46, v46, v234
	v_mul_f32_e32 v47, v47, v234
	v_cvt_pk_bf16_f32 v44, v44, v45
	v_cvt_pk_bf16_f32 v45, v46, v47
	ds_write_b64 v230, v[44:45] offset:96
	v_mul_f32_e32 v48, v48, v234
	v_mul_f32_e32 v49, v49, v234
	v_mul_f32_e32 v50, v50, v234
	v_mul_f32_e32 v51, v51, v234
	v_cvt_pk_bf16_f32 v48, v48, v49
	v_cvt_pk_bf16_f32 v49, v50, v51
	ds_write_b64 v230, v[48:49] offset:128
	v_mul_f32_e32 v52, v52, v234
	v_mul_f32_e32 v53, v53, v234
	v_mul_f32_e32 v54, v54, v234
	v_mul_f32_e32 v55, v55, v234
	v_cvt_pk_bf16_f32 v52, v52, v53
	v_cvt_pk_bf16_f32 v53, v54, v55
	ds_write_b64 v230, v[52:53] offset:160
	v_mul_f32_e32 v56, v56, v234
	v_mul_f32_e32 v57, v57, v234
	v_mul_f32_e32 v58, v58, v234
	v_mul_f32_e32 v59, v59, v234
	v_cvt_pk_bf16_f32 v56, v56, v57
	v_cvt_pk_bf16_f32 v57, v58, v59
	ds_write_b64 v230, v[56:57] offset:192
	v_mul_f32_e32 v60, v60, v234
	v_mul_f32_e32 v61, v61, v234
	v_mul_f32_e32 v62, v62, v234
	v_mul_f32_e32 v63, v63, v234
	v_cvt_pk_bf16_f32 v60, v60, v61
	v_cvt_pk_bf16_f32 v61, v62, v63
	ds_write_b64 v230, v[60:61] offset:224
	v_mul_f32_e32 v64, v64, v235
	v_mul_f32_e32 v65, v65, v235
	v_mul_f32_e32 v66, v66, v235
	v_mul_f32_e32 v67, v67, v235
	v_cvt_pk_bf16_f32 v64, v64, v65
	v_cvt_pk_bf16_f32 v65, v66, v67
	ds_write_b64 v230, v[64:65] offset:4352
	v_mul_f32_e32 v68, v68, v235
	v_mul_f32_e32 v69, v69, v235
	v_mul_f32_e32 v70, v70, v235
	v_mul_f32_e32 v71, v71, v235
	v_cvt_pk_bf16_f32 v68, v68, v69
	v_cvt_pk_bf16_f32 v69, v70, v71
	ds_write_b64 v230, v[68:69] offset:4384
	v_mul_f32_e32 v72, v72, v235
	v_mul_f32_e32 v73, v73, v235
	v_mul_f32_e32 v74, v74, v235
	v_mul_f32_e32 v75, v75, v235
	v_cvt_pk_bf16_f32 v72, v72, v73
	v_cvt_pk_bf16_f32 v73, v74, v75
	ds_write_b64 v230, v[72:73] offset:4416
	v_mul_f32_e32 v76, v76, v235
	v_mul_f32_e32 v77, v77, v235
	v_mul_f32_e32 v78, v78, v235
	v_mul_f32_e32 v79, v79, v235
	v_cvt_pk_bf16_f32 v76, v76, v77
	v_cvt_pk_bf16_f32 v77, v78, v79
	ds_write_b64 v230, v[76:77] offset:4448
	v_mul_f32_e32 v80, v80, v235
	v_mul_f32_e32 v81, v81, v235
	v_mul_f32_e32 v82, v82, v235
	v_mul_f32_e32 v83, v83, v235
	v_cvt_pk_bf16_f32 v80, v80, v81
	v_cvt_pk_bf16_f32 v81, v82, v83
	ds_write_b64 v230, v[80:81] offset:4480
	v_mul_f32_e32 v84, v84, v235
	v_mul_f32_e32 v85, v85, v235
	v_mul_f32_e32 v86, v86, v235
	v_mul_f32_e32 v87, v87, v235
	v_cvt_pk_bf16_f32 v84, v84, v85
	v_cvt_pk_bf16_f32 v85, v86, v87
	ds_write_b64 v230, v[84:85] offset:4512
	v_mul_f32_e32 v88, v88, v235
	v_mul_f32_e32 v89, v89, v235
	v_mul_f32_e32 v90, v90, v235
	v_mul_f32_e32 v91, v91, v235
	v_cvt_pk_bf16_f32 v88, v88, v89
	v_cvt_pk_bf16_f32 v89, v90, v91
	ds_write_b64 v230, v[88:89] offset:4544
	v_mul_f32_e32 v92, v92, v235
	v_mul_f32_e32 v93, v93, v235
	v_mul_f32_e32 v94, v94, v235
	v_mul_f32_e32 v95, v95, v235
	v_cvt_pk_bf16_f32 v92, v92, v93
	v_cvt_pk_bf16_f32 v93, v94, v95
	ds_write_b64 v230, v[92:93] offset:4576
	s_waitcnt lgkmcnt(0)
	ds_read_b128 v[96:99], v231 offset:0
	ds_read_b128 v[100:103], v231 offset:16
	ds_read_b128 v[104:107], v231 offset:32
	ds_read_b128 v[108:111], v231 offset:48
	ds_read_b128 v[112:115], v231 offset:64
	ds_read_b128 v[116:119], v231 offset:80
	ds_read_b128 v[120:123], v231 offset:96
	ds_read_b128 v[124:127], v231 offset:112
	s_waitcnt lgkmcnt(7)
	global_store_dwordx4 v228, v[96:99], s[8:9] offset:0
	s_waitcnt lgkmcnt(6)
	global_store_dwordx4 v228, v[100:103], s[8:9] offset:16
	s_waitcnt lgkmcnt(5)
	global_store_dwordx4 v228, v[104:107], s[8:9] offset:32
	s_waitcnt lgkmcnt(4)
	global_store_dwordx4 v228, v[108:111], s[8:9] offset:48
	s_waitcnt lgkmcnt(3)
	global_store_dwordx4 v228, v[112:115], s[8:9] offset:64
	s_waitcnt lgkmcnt(2)
	global_store_dwordx4 v228, v[116:119], s[8:9] offset:80
	s_waitcnt lgkmcnt(1)
	global_store_dwordx4 v228, v[120:123], s[8:9] offset:96
	s_waitcnt lgkmcnt(0)
	global_store_dwordx4 v228, v[124:127], s[8:9] offset:112
	s_mov_b32 s67, 0
	s_cmp_eq_u32 s68, 1
	s_cbranch_scc1 .Lna_unit
